# v12: v9 + attention block epilogues store 8x dwordx4 via permlane32_swap pairing (was 16x dwordx2); stick-breaking per-step finish flags read with two broadcast ds_read_b128
# speedup vs baseline: 1.0065x; 1.0065x over previous
.LBB0_388:
	s_and_b32 s46, s69, 8
	s_xor_b32 s66, s46, 8
	s_add_i32 s67, 0, 0x10000
	s_lshl_b32 s66, s66, 2
	s_add_i32 s66, s67, s66
	v_mov_b32_e32 v1, s66
	s_waitcnt vmcnt(4)
	s_waitcnt lgkmcnt(0)
	s_barrier
	ds_read_b128 v[68:71], v1
	ds_read_b128 v[72:75], v1 offset:16
	s_mov_b64 s[90:91], -1
	s_waitcnt lgkmcnt(0)
	v_and_b32_e32 v1, v68, v69
	v_and_b32_e32 v2, v70, v71
	v_and_b32_e32 v68, v72, v73
	v_and_b32_e32 v69, v74, v75
	v_and_b32_e32 v1, v1, v2
	v_and_b32_e32 v68, v68, v69
	v_and_b32_e32 v1, v1, v68
	v_and_b32_e32 v1, 1, v1
	v_cmp_eq_u32_e32 vcc, 1, v1
	s_nop 1
	s_and_b64 vcc, exec, vcc
	s_cbranch_vccnz .LBB0_387
	s_max_i32 s66, s1, 3
	s_lshl_b32 s66, s66, 5
	s_addk_i32 s66, 0xffa0
	s_and_b32 s90, s4, 0xc000
	s_ashr_i32 s67, s66, 31
	s_lshl_b64 s[66:67], s[66:67], 12
	s_add_i32 s90, s94, s90
	v_lshl_add_u64 v[68:69], v[174:175], 0, s[66:67]
	s_mov_b32 m0, s90
	s_nop 0
	global_load_lds_dwordx4 v[68:69], off
	v_lshl_add_u64 v[68:69], v[176:177], 0, s[66:67]
	s_add_i32 m0, s90, 0x2000
	s_cmp_gt_i32 s1, s79
	global_load_lds_dwordx4 v[68:69], off
	s_cselect_b64 s[66:67], -1, 0
	s_or_b64 s[66:67], s[66:67], s[86:87]
	s_and_b64 vcc, exec, s[66:67]
	s_cbranch_vccnz .LBB0_394
	s_add_i32 s66, s4, 0xffff4000
	s_and_b32 s66, s66, 0xc000
	s_add_i32 s90, s66, 0
	v_add_u32_e32 v1, s90, v181
	v_add_u32_e32 v2, v1, v183
	ds_read_b128 v[68:71], v2
	v_add_u32_e32 v2, v1, v184
	ds_read_b128 v[84:87], v2
	v_add_u32_e32 v2, v1, v185
	s_cmp_eq_u32 s76, 0
	s_cselect_b64 s[86:87], -1, 0
	s_cmp_lg_u32 s76, 0
	s_waitcnt lgkmcnt(0)
	v_mfma_f32_32x32x16_bf16 v[68:83], v[68:71], v[132:135], 0
	v_mfma_f32_32x32x16_bf16 v[68:83], v[84:87], v[136:139], v[68:83]
	ds_read_b128 v[84:87], v2
	v_add_u32_e32 v2, v1, v186
	ds_read_b128 v[88:91], v2
	v_add_u32_e32 v2, v1, v187
	s_waitcnt lgkmcnt(0)
	v_mfma_f32_32x32x16_bf16 v[68:83], v[84:87], v[140:143], v[68:83]
	ds_read_b128 v[84:87], v2
	v_add_u32_e32 v2, v1, v188
	v_mfma_f32_32x32x16_bf16 v[68:83], v[88:91], v[144:147], v[68:83]
	ds_read_b128 v[88:91], v2
	v_add_u32_e32 v2, v1, v189
	v_add_u32_e32 v1, v1, v190
	s_waitcnt lgkmcnt(0)
	v_mfma_f32_32x32x16_bf16 v[68:83], v[84:87], v[148:151], v[68:83]
	ds_read_b128 v[84:87], v2
	v_mfma_f32_32x32x16_bf16 v[68:83], v[88:91], v[152:155], v[68:83]
	ds_read_b128 v[88:91], v1
	s_waitcnt lgkmcnt(0)
	v_mfma_f32_32x32x16_bf16 v[68:83], v[84:87], v[156:159], v[68:83]
	v_mfma_f32_32x32x16_bf16 v[68:83], v[88:91], v[160:163], v[68:83]
	s_nop 11
	v_exp_f32_e64 v1, -|v68|
	v_exp_f32_e64 v84, -|v69|
	v_exp_f32_e64 v88, -|v71|
	v_exp_f32_e64 v86, -|v70|
	v_exp_f32_e64 v90, -|v72|
	v_exp_f32_e64 v92, -|v73|
	v_add_f32_e32 v1, 1.0, v1
	v_add_f32_e32 v84, 1.0, v84
	v_add_f32_e32 v88, 1.0, v88
	v_log_f32_e32 v1, v1
	v_exp_f32_e64 v94, -|v74|
	v_add_f32_e32 v86, 1.0, v86
	v_add_f32_e32 v90, 1.0, v90
	v_log_f32_e32 v84, v84
	v_log_f32_e32 v88, v88
	v_log_f32_e32 v86, v86
	v_log_f32_e32 v90, v90
	v_max_f32_e32 v2, 0, v68
	v_add_f32_e32 v92, 1.0, v92
	v_max_f32_e32 v85, 0, v69
	v_max_f32_e32 v89, 0, v71
	v_log_f32_e32 v92, v92
	v_add_f32_e32 v1, v2, v1
	v_max_f32_e32 v87, 0, v70
	v_max_f32_e32 v91, 0, v72
	v_add_f32_e32 v94, 1.0, v94
	v_add_f32_e32 v2, v85, v84
	v_add_f32_e32 v85, v89, v88
	v_cndmask_b32_e64 v89, 0, -v1, s[10:11]
	v_log_f32_e32 v94, v94
	v_add_f32_e32 v84, v87, v86
	v_add_f32_e32 v86, v91, v90
	v_cndmask_b32_e64 v90, 0, -v2, s[12:13]
	v_cndmask_b32_e64 v98, -v1, v89, s[86:87]
	v_max_f32_e32 v93, 0, v73
	v_cndmask_b32_e64 v91, 0, -v84, s[14:15]
	v_cndmask_b32_e64 v90, -v2, v90, s[86:87]
	v_add_f32_e32 v1, 0, v98
	v_exp_f32_e64 v96, -|v75|
	v_add_f32_e32 v87, v93, v92
	v_cndmask_b32_e64 v92, 0, -v85, s[16:17]
	v_cndmask_b32_e64 v91, -v84, v91, s[86:87]
	v_add_f32_e32 v1, v90, v1
	v_max_f32_e32 v95, 0, v74
	v_cndmask_b32_e64 v93, 0, -v86, s[18:19]
	v_cndmask_b32_e64 v92, -v85, v92, s[86:87]
	v_add_f32_e32 v1, v91, v1
	v_add_f32_e32 v88, v95, v94
	v_cndmask_b32_e64 v94, 0, -v87, s[20:21]
	v_cndmask_b32_e64 v93, -v86, v93, s[86:87]
	v_add_f32_e32 v1, v92, v1
	v_cndmask_b32_e64 v87, -v87, v94, s[86:87]
	v_add_f32_e32 v1, v93, v1
	v_add_f32_e32 v96, 1.0, v96
	v_add_f32_e32 v86, v87, v1
	v_exp_f32_e64 v1, -|v76|
	v_log_f32_e32 v96, v96
	v_max_f32_e32 v97, 0, v75
	v_add_f32_e32 v1, 1.0, v1
	v_add_f32_e32 v2, v97, v96
	v_log_f32_e32 v1, v1
	v_cndmask_b32_e64 v84, 0, -v2, s[24:25]
	v_cndmask_b32_e64 v94, -v2, v84, s[86:87]
	v_exp_f32_e64 v84, -|v77|
	v_max_f32_e32 v2, 0, v76
	v_add_f32_e32 v1, v2, v1
	v_cndmask_b32_e64 v2, 0, -v1, s[26:27]
	v_cndmask_b32_e64 v89, -v1, v2, s[86:87]
	v_add_f32_e32 v1, 1.0, v84
	v_log_f32_e32 v1, v1
	v_max_f32_e32 v84, 0, v77
	v_add_f32_e32 v2, 0, v89
	v_add_f32_e32 v1, v84, v1
	v_exp_f32_e64 v84, -|v78|
	v_cndmask_b32_e64 v85, 0, -v1, s[28:29]
	v_cndmask_b32_e64 v96, -v1, v85, s[86:87]
	v_add_f32_e32 v1, v96, v2
	v_add_f32_e32 v2, 1.0, v84
	v_log_f32_e32 v2, v2
	v_exp_f32_e64 v85, -|v79|
	v_max_f32_e32 v84, 0, v78
	v_add_f32_e32 v2, v84, v2
	v_cndmask_b32_e64 v84, 0, -v2, s[30:31]
	v_cndmask_b32_e64 v97, -v2, v84, s[86:87]
	v_add_f32_e32 v2, 1.0, v85
	v_log_f32_e32 v2, v2
	v_max_f32_e32 v84, 0, v79
	v_add_f32_e32 v1, v97, v1
	v_add_f32_e32 v2, v84, v2
	v_exp_f32_e64 v84, -|v80|
	v_cndmask_b32_e64 v85, 0, -v2, s[34:35]
	v_cndmask_b32_e64 v99, -v2, v85, s[86:87]
	v_exp_f32_e64 v85, -|v81|
	v_add_f32_e32 v2, 1.0, v84
	v_log_f32_e32 v2, v2
	v_max_f32_e32 v84, 0, v80
	v_add_f32_e32 v1, v99, v1
	v_add_f32_e32 v2, v84, v2
	v_cndmask_b32_e64 v84, 0, -v2, s[36:37]
	v_cndmask_b32_e64 v100, -v2, v84, s[86:87]
	v_add_f32_e32 v2, 1.0, v85
	v_log_f32_e32 v2, v2
	v_max_f32_e32 v84, 0, v81
	v_add_f32_e32 v1, v100, v1
	v_add_f32_e32 v2, v84, v2
	v_exp_f32_e64 v84, -|v82|
	v_cndmask_b32_e64 v85, 0, -v2, s[38:39]
	v_cndmask_b32_e64 v101, -v2, v85, s[86:87]
	v_exp_f32_e64 v85, -|v83|
	v_add_f32_e32 v2, 1.0, v84
	v_log_f32_e32 v2, v2
	v_max_f32_e32 v84, 0, v82
	v_add_f32_e32 v1, v101, v1
	v_add_f32_e32 v2, v84, v2
	v_cndmask_b32_e64 v84, 0, -v2, s[40:41]
	v_cndmask_b32_e64 v102, -v2, v84, s[86:87]
	v_add_f32_e32 v2, 1.0, v85
	v_log_f32_e32 v2, v2
	v_max_f32_e32 v84, 0, v83
	v_add_f32_e32 v1, v102, v1
	v_add_f32_e32 v2, v84, v2
	v_cndmask_b32_e64 v84, 0, -v2, s[42:43]
	v_cndmask_b32_e64 v2, -v2, v84, s[86:87]
	v_add_f32_e32 v84, v2, v1
	v_mov_b32_e32 v1, v84
	v_mov_b32_e32 v85, v84
	s_nop 1
	v_permlane32_swap_b32_e32 v1, v85
	v_cndmask_b32_e64 v85, v1, v85, s[2:3]
	v_add_f32_e32 v1, v173, v85
	v_cndmask_b32_e64 v103, v173, v1, s[6:7]
	v_add_f32_e32 v105, v1, v84
	v_add_f32_e32 v1, v83, v2
	v_add_f32_e32 v83, v103, v2
	v_add_f32_e32 v2, v82, v102
	v_add_f32_e32 v82, v102, v83
	v_add_f32_e32 v81, v81, v101
	v_add_f32_e32 v81, v81, v82
	v_add_f32_e32 v82, v101, v82
	v_add_f32_e32 v80, v80, v100
	v_add_f32_e32 v80, v80, v82
	v_add_f32_e32 v82, v100, v82
	v_add_f32_e32 v79, v79, v99
	v_add_f32_e32 v79, v79, v82
	v_add_f32_e32 v82, v99, v82
	v_add_f32_e32 v78, v78, v97
	v_cndmask_b32_e64 v95, 0, -v88, s[22:23]
	v_add_f32_e32 v78, v78, v82
	v_add_f32_e32 v82, v97, v82
	v_add_f32_e32 v77, v77, v96
	v_add_f32_e32 v77, v77, v82
	v_add_f32_e32 v82, v96, v82
	v_add_f32_e32 v76, v76, v89
	v_cndmask_b32_e64 v88, -v88, v95, s[86:87]
	v_add_f32_e32 v76, v76, v82
	v_add_f32_e32 v82, v88, v86
	v_add_f32_e32 v82, v94, v82
	v_mov_b32_e32 v86, v82
	v_mov_b32_e32 v89, v82
	s_nop 1
	v_permlane32_swap_b32_e32 v86, v89
	v_add_f32_e32 v104, v173, v84
	v_cndmask_b32_e64 v86, v86, v89, s[2:3]
	v_add_f32_e32 v2, v83, v2
	v_add_f32_e32 v83, v104, v85
	v_add_f32_e32 v89, v105, v86
	v_add_f32_e32 v75, v75, v94
	v_cndmask_b32_e64 v89, v83, v89, s[6:7]
	v_add_f32_e32 v75, v75, v89
	v_exp_f32_e32 v83, v75
	v_mov_b32_e32 v75, v94
	v_pk_add_f32 v[74:75], v[74:75], v[88:89]
	v_add_f32_e32 v73, v73, v87
	v_add_f32_e32 v74, v74, v75
	v_add_f32_e32 v75, v88, v75
	v_add_f32_e32 v73, v73, v75
	v_add_f32_e32 v75, v87, v75
	v_add_f32_e32 v72, v72, v93
	v_add_f32_e32 v72, v72, v75
	v_add_f32_e32 v75, v93, v75
	v_add_f32_e32 v71, v71, v92
	v_add_f32_e32 v71, v71, v75
	v_add_f32_e32 v75, v92, v75
	v_add_f32_e32 v70, v70, v91
	v_add_f32_e32 v70, v70, v75
	v_add_f32_e32 v75, v91, v75
	v_add_f32_e32 v69, v69, v90
	v_add_f32_e32 v69, v69, v75
	v_add_f32_e32 v75, v90, v75
	v_add_f32_e32 v68, v68, v98
	v_add_f32_e32 v1, v103, v1
	v_add_f32_e32 v68, v68, v75
	v_exp_f32_e32 v1, v1
	v_exp_f32_e32 v2, v2
	v_exp_f32_e32 v81, v81
	v_exp_f32_e32 v80, v80
	v_exp_f32_e32 v79, v79
	v_exp_f32_e32 v78, v78
	v_exp_f32_e32 v77, v77
	v_exp_f32_e32 v76, v76
	v_exp_f32_e32 v74, v74
	v_exp_f32_e32 v73, v73
	v_exp_f32_e32 v72, v72
	v_exp_f32_e32 v71, v71
	v_exp_f32_e32 v70, v70
	v_exp_f32_e32 v69, v69
	v_exp_f32_e32 v68, v68
	s_cbranch_scc1 .LBB0_392
	s_or_b64 vcc, s[12:13], s[10:11]
	v_cndmask_b32_e32 v68, 0, v68, vcc
	s_or_b64 vcc, s[16:17], s[14:15]
	v_cndmask_b32_e32 v70, 0, v70, vcc
	s_or_b64 vcc, s[20:21], s[18:19]
	v_cndmask_b32_e32 v72, 0, v72, vcc
	s_or_b64 vcc, s[24:25], s[22:23]
	v_cndmask_b32_e32 v74, 0, v74, vcc
	s_or_b64 vcc, s[28:29], s[26:27]
	v_cndmask_b32_e32 v76, 0, v76, vcc
	s_or_b64 vcc, s[34:35], s[30:31]
	v_cndmask_b32_e32 v78, 0, v78, vcc
	s_or_b64 vcc, s[38:39], s[36:37]
	v_cndmask_b32_e32 v80, 0, v80, vcc
	s_or_b64 vcc, s[42:43], s[40:41]
	v_cndmask_b32_e64 v69, 0, v69, s[12:13]
	v_cndmask_b32_e64 v71, 0, v71, s[16:17]
	v_cndmask_b32_e64 v73, 0, v73, s[20:21]
	v_cndmask_b32_e64 v83, 0, v83, s[24:25]
	v_cndmask_b32_e64 v77, 0, v77, s[28:29]
	v_cndmask_b32_e64 v79, 0, v79, s[34:35]
	v_cndmask_b32_e64 v81, 0, v81, s[38:39]
	v_cndmask_b32_e64 v1, 0, v1, s[42:43]
	v_cndmask_b32_e32 v2, 0, v2, vcc

.LBB0_397:
	v_lshl_add_u64 v[68:69], v[178:179], 1, s[74:75]
	s_mov_b32 s1, s77
	v_lshl_add_u64 v[68:69], v[68:69], 0, s[0:1]
	v_lshlrev_b32_e32 v2, 1, v166
	s_waitcnt vmcnt(0)
	v_lshl_add_u64 v[68:69], v[68:69], 0, v[2:3]
	v_mbcnt_lo_u32_b32 v1, -1, 0
	v_mbcnt_hi_u32_b32 v1, -1, v1
	v_and_b32_e32 v1, 32, v1
	v_lshrrev_b32_e32 v2, 2, v1
	v_lshl_add_u64 v[68:69], v[68:69], 0, v[2:3]
	s_waitcnt lgkmcnt(0)
	s_barrier
	v_cvt_pk_bf16_f32 v212, v36, v37
	v_cvt_pk_bf16_f32 v213, v38, v39
	v_cvt_pk_bf16_f32 v214, v40, v41
	v_cvt_pk_bf16_f32 v215, v42, v43
	s_nop 1
	v_permlane32_swap_b32_e32 v212, v214
	v_permlane32_swap_b32_e32 v213, v215
	global_store_dwordx4 v[68:69], v[212:215], off
	v_cvt_pk_bf16_f32 v216, v44, v45
	v_cvt_pk_bf16_f32 v217, v46, v47
	v_cvt_pk_bf16_f32 v218, v48, v49
	v_cvt_pk_bf16_f32 v219, v50, v51
	s_nop 1
	v_permlane32_swap_b32_e32 v216, v218
	v_permlane32_swap_b32_e32 v217, v219
	global_store_dwordx4 v[68:69], v[216:219], off offset:32
	v_cvt_pk_bf16_f32 v212, v52, v53
	v_cvt_pk_bf16_f32 v213, v54, v55
	v_cvt_pk_bf16_f32 v214, v56, v57
	v_cvt_pk_bf16_f32 v215, v58, v59
	s_nop 1
	v_permlane32_swap_b32_e32 v212, v214
	v_permlane32_swap_b32_e32 v213, v215
	global_store_dwordx4 v[68:69], v[212:215], off offset:64
	v_cvt_pk_bf16_f32 v216, v60, v61
	v_cvt_pk_bf16_f32 v217, v62, v63
	v_cvt_pk_bf16_f32 v218, v64, v65
	v_cvt_pk_bf16_f32 v219, v66, v67
	s_nop 1
	v_permlane32_swap_b32_e32 v216, v218
	v_permlane32_swap_b32_e32 v217, v219
	global_store_dwordx4 v[68:69], v[216:219], off offset:96
	v_cvt_pk_bf16_f32 v212, v20, v21
	v_cvt_pk_bf16_f32 v213, v22, v23
	v_cvt_pk_bf16_f32 v214, v24, v25
	v_cvt_pk_bf16_f32 v215, v26, v27
	s_nop 1
	v_permlane32_swap_b32_e32 v212, v214
	v_permlane32_swap_b32_e32 v213, v215
	global_store_dwordx4 v[68:69], v[212:215], off offset:128
	v_cvt_pk_bf16_f32 v216, v28, v29
	v_cvt_pk_bf16_f32 v217, v30, v31
	v_cvt_pk_bf16_f32 v218, v32, v33
	v_cvt_pk_bf16_f32 v219, v34, v35
	s_nop 1
	v_permlane32_swap_b32_e32 v216, v218
	v_permlane32_swap_b32_e32 v217, v219
	global_store_dwordx4 v[68:69], v[216:219], off offset:160
	v_cvt_pk_bf16_f32 v212, v4, v5
	v_cvt_pk_bf16_f32 v213, v6, v7
	v_cvt_pk_bf16_f32 v214, v8, v9
	v_cvt_pk_bf16_f32 v215, v10, v11
	s_nop 1
	v_permlane32_swap_b32_e32 v212, v214
	v_permlane32_swap_b32_e32 v213, v215
	global_store_dwordx4 v[68:69], v[212:215], off offset:192
	v_cvt_pk_bf16_f32 v216, v12, v13
	v_cvt_pk_bf16_f32 v217, v14, v15
	v_cvt_pk_bf16_f32 v218, v16, v17
	v_cvt_pk_bf16_f32 v219, v18, v19
	s_nop 1
	v_permlane32_swap_b32_e32 v216, v218
	v_permlane32_swap_b32_e32 v217, v219
	global_store_dwordx4 v[68:69], v[216:219], off offset:224
	s_mov_b64 s[0:1], 0

.LBB0_412:
	v_mov_b32_e32 v1, v133
	v_mov_b32_e32 v2, v133
	s_lshl_b32 s0, s79, 7
	v_lshlrev_b64 v[4:5], 10, v[130:131]
	v_permlane32_swap_b32_e32 v1, v2
	v_cndmask_b32_e64 v1, v1, v2, s[2:3]
	v_lshl_add_u64 v[4:5], v[4:5], 1, s[72:73]
	s_lshl_b32 s76, s0, 1
	v_add_f32_e32 v1, v133, v1
	v_lshl_add_u64 v[4:5], v[4:5], 0, s[76:77]
	v_lshlrev_b32_e32 v2, 1, v166
	v_lshl_add_u64 v[4:5], v[4:5], 0, v[2:3]
	v_mbcnt_lo_u32_b32 v6, -1, 0
	v_mbcnt_hi_u32_b32 v6, -1, v6
	v_and_b32_e32 v6, 32, v6
	v_lshrrev_b32_e32 v6, 2, v6
	v_mov_b32_e32 v7, 0
	v_lshl_add_u64 v[4:5], v[4:5], 0, v[6:7]
	v_div_scale_f32 v2, s[0:1], v1, v1, 1.0
	v_rcp_f32_e32 v6, v2
	s_waitcnt vmcnt(0)
	s_waitcnt lgkmcnt(0)
	s_barrier
	v_fma_f32 v7, -v2, v6, 1.0
	v_fmac_f32_e32 v6, v7, v6
	v_div_scale_f32 v7, vcc, 1.0, v1, 1.0
	v_mul_f32_e32 v8, v7, v6
	v_fma_f32 v9, -v2, v8, v7
	v_fmac_f32_e32 v8, v9, v6
	v_fma_f32 v2, -v2, v8, v7
	v_div_fmas_f32 v2, v2, v6, v8
	v_div_fixup_f32 v2, v2, v1, 1.0
	v_pk_mul_f32 v[6:7], v[66:67], v[2:3] op_sel_hi:[1,0]
	v_pk_mul_f32 v[8:9], v[68:69], v[2:3] op_sel_hi:[1,0]
	v_pk_mul_f32 v[10:11], v[70:71], v[2:3] op_sel_hi:[1,0]
	v_pk_mul_f32 v[12:13], v[72:73], v[2:3] op_sel_hi:[1,0]
	v_cvt_pk_bf16_f32 v6, v6, v7
	v_cvt_pk_bf16_f32 v7, v8, v9
	v_cvt_pk_bf16_f32 v8, v10, v11
	v_cvt_pk_bf16_f32 v9, v12, v13
	s_nop 1
	v_permlane32_swap_b32_e32 v6, v8
	v_permlane32_swap_b32_e32 v7, v9
	global_store_dwordx4 v[4:5], v[6:9], off
	v_pk_mul_f32 v[212:213], v[74:75], v[2:3] op_sel_hi:[1,0]
	v_pk_mul_f32 v[214:215], v[76:77], v[2:3] op_sel_hi:[1,0]
	v_pk_mul_f32 v[216:217], v[78:79], v[2:3] op_sel_hi:[1,0]
	v_pk_mul_f32 v[218:219], v[80:81], v[2:3] op_sel_hi:[1,0]
	v_cvt_pk_bf16_f32 v212, v212, v213
	v_cvt_pk_bf16_f32 v213, v214, v215
	v_cvt_pk_bf16_f32 v214, v216, v217
	v_cvt_pk_bf16_f32 v215, v218, v219
	s_nop 1
	v_permlane32_swap_b32_e32 v212, v214
	v_permlane32_swap_b32_e32 v213, v215
	global_store_dwordx4 v[4:5], v[212:215], off offset:32
	v_pk_mul_f32 v[6:7], v[50:51], v[2:3] op_sel_hi:[1,0]
	v_pk_mul_f32 v[8:9], v[52:53], v[2:3] op_sel_hi:[1,0]
	v_pk_mul_f32 v[10:11], v[54:55], v[2:3] op_sel_hi:[1,0]
	v_pk_mul_f32 v[12:13], v[56:57], v[2:3] op_sel_hi:[1,0]
	v_cvt_pk_bf16_f32 v6, v6, v7
	v_cvt_pk_bf16_f32 v7, v8, v9
	v_cvt_pk_bf16_f32 v8, v10, v11
	v_cvt_pk_bf16_f32 v9, v12, v13
	s_nop 1
	v_permlane32_swap_b32_e32 v6, v8
	v_permlane32_swap_b32_e32 v7, v9
	global_store_dwordx4 v[4:5], v[6:9], off offset:64
	v_pk_mul_f32 v[212:213], v[58:59], v[2:3] op_sel_hi:[1,0]
	v_pk_mul_f32 v[214:215], v[60:61], v[2:3] op_sel_hi:[1,0]
	v_pk_mul_f32 v[216:217], v[62:63], v[2:3] op_sel_hi:[1,0]
	v_pk_mul_f32 v[218:219], v[64:65], v[2:3] op_sel_hi:[1,0]
	v_cvt_pk_bf16_f32 v212, v212, v213
	v_cvt_pk_bf16_f32 v213, v214, v215
	v_cvt_pk_bf16_f32 v214, v216, v217
	v_cvt_pk_bf16_f32 v215, v218, v219
	s_nop 1
	v_permlane32_swap_b32_e32 v212, v214
	v_permlane32_swap_b32_e32 v213, v215
	global_store_dwordx4 v[4:5], v[212:215], off offset:96
	v_pk_mul_f32 v[6:7], v[34:35], v[2:3] op_sel_hi:[1,0]
	v_pk_mul_f32 v[8:9], v[36:37], v[2:3] op_sel_hi:[1,0]
	v_pk_mul_f32 v[10:11], v[38:39], v[2:3] op_sel_hi:[1,0]
	v_pk_mul_f32 v[12:13], v[40:41], v[2:3] op_sel_hi:[1,0]
	v_cvt_pk_bf16_f32 v6, v6, v7
	v_cvt_pk_bf16_f32 v7, v8, v9
	v_cvt_pk_bf16_f32 v8, v10, v11
	v_cvt_pk_bf16_f32 v9, v12, v13
	s_nop 1
	v_permlane32_swap_b32_e32 v6, v8
	v_permlane32_swap_b32_e32 v7, v9
	global_store_dwordx4 v[4:5], v[6:9], off offset:128
	v_pk_mul_f32 v[212:213], v[42:43], v[2:3] op_sel_hi:[1,0]
	v_pk_mul_f32 v[214:215], v[44:45], v[2:3] op_sel_hi:[1,0]
	v_pk_mul_f32 v[216:217], v[46:47], v[2:3] op_sel_hi:[1,0]
	v_pk_mul_f32 v[218:219], v[48:49], v[2:3] op_sel_hi:[1,0]
	v_cvt_pk_bf16_f32 v212, v212, v213
	v_cvt_pk_bf16_f32 v213, v214, v215
	v_cvt_pk_bf16_f32 v214, v216, v217
	v_cvt_pk_bf16_f32 v215, v218, v219
	s_nop 1
	v_permlane32_swap_b32_e32 v212, v214
	v_permlane32_swap_b32_e32 v213, v215
	global_store_dwordx4 v[4:5], v[212:215], off offset:160
	v_pk_mul_f32 v[6:7], v[18:19], v[2:3] op_sel_hi:[1,0]
	v_pk_mul_f32 v[8:9], v[20:21], v[2:3] op_sel_hi:[1,0]
	v_pk_mul_f32 v[10:11], v[22:23], v[2:3] op_sel_hi:[1,0]
	v_pk_mul_f32 v[12:13], v[24:25], v[2:3] op_sel_hi:[1,0]
	v_cvt_pk_bf16_f32 v6, v6, v7
	v_cvt_pk_bf16_f32 v7, v8, v9
	v_cvt_pk_bf16_f32 v8, v10, v11
	v_cvt_pk_bf16_f32 v9, v12, v13
	s_nop 1
	v_permlane32_swap_b32_e32 v6, v8
	v_permlane32_swap_b32_e32 v7, v9
	global_store_dwordx4 v[4:5], v[6:9], off offset:192
	v_pk_mul_f32 v[212:213], v[26:27], v[2:3] op_sel_hi:[1,0]
	v_pk_mul_f32 v[214:215], v[28:29], v[2:3] op_sel_hi:[1,0]
	v_pk_mul_f32 v[216:217], v[30:31], v[2:3] op_sel_hi:[1,0]
	v_pk_mul_f32 v[218:219], v[32:33], v[2:3] op_sel_hi:[1,0]
	v_cvt_pk_bf16_f32 v212, v212, v213
	v_cvt_pk_bf16_f32 v213, v214, v215
	v_cvt_pk_bf16_f32 v214, v216, v217
	v_cvt_pk_bf16_f32 v215, v218, v219
	s_nop 1
	v_permlane32_swap_b32_e32 v212, v214
	v_permlane32_swap_b32_e32 v213, v215
	global_store_dwordx4 v[4:5], v[212:215], off offset:224
	s_and_saveexec_b64 s[0:1], s[6:7]
	s_cbranch_execz .LBB0_374
	v_log_f32_e32 v1, v1
	v_readlane_b32 s66, v254, 32
	v_lshlrev_b64 v[4:5], 5, v[130:131]
	v_readlane_b32 s67, v254, 33
	s_lshl_b32 s76, s79, 2
	v_add_f32_e32 v1, v138, v1
	v_lshl_add_u64 v[4:5], s[66:67], 0, v[4:5]
	v_lshl_add_u64 v[4:5], v[4:5], 0, s[76:77]
	global_store_dword v[4:5], v1, off
	s_branch .LBB0_374
